# attention tile body hand-rewritten: LDS reads issued up front with counted lgkmcnt, v_max3 tree, fmamk+exp2 with bias folded, packed sum tree, interleaved PV chains; Q frags drained before the loop
# speedup vs baseline: 1.0173x; 1.0173x over previous
; #define LAS __attribute__((address_space(3)))
; #define AB_LOAD(jj) do { const long o_ = (long)(tc0 + (jj)) * 64 * 1024; kreg0 = *(const u32x4*)(kbase + o_); vreg0 = *(const u32x4*)(vbase + o_); kreg1 = *(const u32x4*)(kbase + o_ + 64); vreg1 = *(const u32x4*)(vbase + o_ + 64); } while (0)
; #define AB_STORE(jj) do { LAS unsigned char* b_ = lds + ((jj) & 1) * AB_BUF + lrow * ATT_VP + lch * 16; *(LAS u32x4*)b_ = kreg0; *(LAS u32x4*)(b_ + 9216) = vreg0; *(LAS u32x4*)(b_ + AB_HB) = kreg1; *(LAS u32x4*)(b_ + AB_HB + 9216) = vreg1; } while (0)
; __device__ __forceinline__ void attn_block_unit(LAS unsigned char* lds, const bf16* QB, bf16* OB, const bf16* KB, const bf16* VB, int sb, int hp, int cp, const float* tab, int tid) {
;     const int lane = tid & 63, w = __builtin_amdgcn_readfirstlane(tid >> 6), r32 = lane & 31, hi = lane >> 5, g16 = lane >> 4, i16 = lane & 15;
;     const int hsel = w >> 2, csel = (w >> 1) & 1, qh = w & 1, h = 2 * hp + hsel, c = 2 * cp + csel;
;     LAS float* btab = (LAS float*)(lds + AB_TAB + hsel * 1040);
;     __syncthreads();
;     for (int i = tid; i < 2 * 257; i += NTHREADS) { const int hh = i >= 257, k = i - 257 * hh; ((LAS float*)(lds + AB_TAB + hh * 1040))[k] = tab[(2 * hp + hh) * 257 + k]; }
;     const float cb = tab[h * 257 + 256];
;     const size_t hoff = (size_t)h * 64;
;     const bf16* Qc = QB + ((size_t)sb * 2048 + (size_t)c * 64) * 1024 + hoff;
;     bf16x8 qfr[4];
; #pragma unroll
;     for (int d0 = 0; d0 < 4; ++d0) qfr[d0] = *(const bf16x8*)(Qc + (size_t)(32 * qh + r32) * 1024 + 16 * d0 + 8 * hi);
;     f32x16 oT[2];
; #pragma unroll
;     for (int a = 0; a < 2; ++a)
; #pragma unroll
;         for (int r = 0; r < 16; ++r) oT[a][r] = 0.f;
;     float mrun = -1e30f, lrun = 0.f;
;     const int traddr = ((g16 >> 1) * 4 + (i16 >> 2)) * ATT_VP + ((g16 & 1) * 16 + (i16 & 3) * 4) * 2;
;     const int lrow = tid >> 3, lch = tid & 7;
;     const int tc0 = 2 * cp - 8, j0 = tc0 < 0 ? -tc0 : 0;
;     const size_t pbase = ((size_t)sb * 2048 + lrow) * 1024 + (size_t)(2 * hp) * 64 + lch * 8;
;     const bf16* kbase = KB + pbase; const bf16* vbase = VB + pbase;
;     u32x4 kreg0, vreg0, kreg1, vreg1;
;     ...
;     AB_LOAD(j0); AB_STORE(j0);
.LBB0_542:
	s_or_b64 exec, exec, s[26:27]
	s_lshr_b32 s15, s40, 6
	s_lshr_b32 s6, s40, 3
	s_and_b32 s14, s15, 12
	s_and_b32 s15, s15, 0x3fffffc
	s_add_i32 s14, s14, s6
	s_ashr_i32 s29, s2, 8
	s_add_i32 s15, s15, s6
	s_and_b32 s28, s14, 15
	s_add_i32 s14, s29, s3
	s_and_b32 s6, s15, 15
	s_bfe_u32 s30, s2, 0x10007
	s_bfe_u32 s31, s2, 0x10006
	s_mul_i32 s2, s29, 0x410
	s_lshl_b32 s42, s6, 1
	s_lshl_b32 s6, s39, 10
	s_mul_i32 s26, s14, 0x101
	s_lshl_b32 s41, s28, 1
	s_add_i32 s2, s2, 0
	s_and_b32 s6, s6, 0xe00000
	s_and_b32 s15, s40, 0x380
	s_ashr_i32 s27, s26, 31
	s_or_b32 s3, s30, s41
	s_add_i32 s2, s2, 0x12000
	s_or_b32 s78, s15, s6
	s_lshl_b64 s[26:27], s[26:27], 2
	s_add_u32 s4, s4, s26
	s_addc_u32 s5, s5, s27
	s_lshl_b32 s6, s40, 11
	v_lshl_add_u64 v[12:13], s[78:79], 0, v[186:187]
	s_and_b32 s78, s6, 0x3800
	s_lshl_b32 s3, s3, 6
	s_ashr_i32 s15, s14, 31
	s_or_b32 s3, s3, s78
	global_load_dword v190, v3, s[4:5] offset:1024
	s_lshl_b64 s[4:5], s[14:15], 6
	s_lshl_b32 s6, s3, 11
	s_add_u32 s6, s16, s6
	s_addc_u32 s26, s17, 0
	s_lshl_b64 s[14:15], s[14:15], 7
	s_add_u32 s14, s6, s14
	s_addc_u32 s15, s26, s15
	s_sub_i32 s6, 8, s41
	s_cmp_lt_u32 s28, 4
	v_lshl_add_u64 v[4:5], s[78:79], 0, v[178:179]
	s_cselect_b32 s6, s6, 0
	v_lshlrev_b64 v[4:5], 10, v[4:5]
	s_add_i32 s26, s41, s6
	v_lshl_or_b32 v2, s7, 7, v4
	v_or_b32_e32 v4, v2, v180
	s_add_i32 s26, s26, -8
	v_lshlrev_b64 v[4:5], 1, v[4:5]
	s_ashr_i32 s27, s26, 31
	v_lshl_add_u64 v[6:7], s[18:19], 0, v[4:5]
	v_lshl_add_u64 v[4:5], s[20:21], 0, v[4:5]
	s_lshl_b64 s[26:27], s[26:27], 17
	v_lshlrev_b32_e32 v2, 1, v134
	v_lshl_add_u64 v[6:7], v[6:7], 0, s[26:27]
	v_lshl_add_u64 v[4:5], v[4:5], 0, s[26:27]
	v_lshl_or_b32 v2, s31, 16, v2
	global_load_dwordx4 v[100:103], v[6:7], off
	global_load_dwordx4 v[112:115], v[4:5], off
	global_load_dwordx4 v[116:119], v[6:7], off offset:128
	global_load_dwordx4 v[128:131], v[4:5], off offset:128
	v_lshl_add_u64 v[4:5], s[14:15], 0, v[2:3]
	v_mov_b32_e32 v189, v3
	v_lshl_add_u64 v[4:5], v[4:5], 0, v[188:189]
	global_load_dwordx4 v[104:107], v[4:5], off
	global_load_dwordx4 v[108:111], v[4:5], off offset:32
	global_load_dwordx4 v[120:123], v[4:5], off offset:64
	global_load_dwordx4 v[124:127], v[4:5], off offset:96
	s_lshl_b32 s7, s31, 5
	s_lshl_b32 s15, s30, 6
	s_or_b32 s14, s7, s15
	s_lshl_b32 s26, s6, 6
	s_add_i32 s27, s6, s42
	v_add_u32_e32 v11, s14, v139
	v_or_b32_e32 v14, s26, v152
	s_add_i32 s14, s27, -8
	s_mulk_i32 s29, 0x4800
	v_subrev_u32_e32 v189, s26, v11
	v_sub_u32_e32 v11, s15, v14
	s_ashr_i32 s15, s14, 31
	s_add_i32 s28, s29, 0
	s_sub_i32 s29, 0, s30
	s_lshl_b64 s[14:15], s[14:15], 17
	s_add_u32 s14, s37, s14
	s_addc_u32 s15, s38, s15
	v_mov_b32_e32 v16, v3
	v_mov_b32_e32 v17, v3
	v_mov_b32_e32 v4, v3
	v_mov_b32_e32 v5, v3
	v_mov_b32_e32 v6, v3
	v_mov_b32_e32 v7, v3
	v_mov_b32_e32 v8, v3
	v_mov_b32_e32 v9, v3
	v_mov_b32_e32 v10, v3
	v_mov_b32_e32 v2, v3
	v_add_u32_e32 v213, s7, v11
	v_lshl_add_u64 v[192:193], v[12:13], 1, s[14:15]
	v_mov_b32_e32 v11, v3
	v_mov_b32_e32 v12, v3
	v_mov_b32_e32 v13, v3
	v_mov_b32_e32 v14, v3
	v_mov_b32_e32 v15, v3
	v_mov_b64_e32 v[34:35], v[16:17]
	v_mov_b64_e32 v[32:33], v[14:15]
	v_mov_b64_e32 v[30:31], v[12:13]
	v_mov_b64_e32 v[28:29], v[10:11]
	v_mov_b64_e32 v[26:27], v[8:9]
	v_mov_b64_e32 v[24:25], v[6:7]
	v_mov_b64_e32 v[22:23], v[4:5]
	v_mov_b64_e32 v[20:21], v[2:3]
	v_mov_b64_e32 v[18:19], v[16:17]
	v_mov_b32_e32 v214, 0
	v_mov_b32_e32 v215, 0xf149f2ca
	v_mov_b64_e32 v[16:17], v[14:15]
	v_mov_b64_e32 v[14:15], v[12:13]
	v_mov_b64_e32 v[12:13], v[10:11]
	s_waitcnt vmcnt(8)
	v_mov_b32_e32 v194, v190
	v_mov_b32_e32 v195, v190
	v_mov_b64_e32 v[10:11], v[8:9]
	v_mov_b64_e32 v[8:9], v[6:7]
	v_mov_b64_e32 v[6:7], v[4:5]
	v_mov_b64_e32 v[4:5], v[2:3]
	s_waitcnt vmcnt(7)
	ds_write_b128 v165, v[100:103]
	s_waitcnt vmcnt(6)
	ds_write_b128 v165, v[112:115] offset:9216
	s_waitcnt vmcnt(5)
	ds_write_b128 v165, v[116:119] offset:18432
	s_waitcnt vmcnt(4)
	ds_write_b128 v165, v[128:131] offset:27648
	s_waitcnt vmcnt(0)

; #define LAS __attribute__((address_space(3)))
; __device__ __forceinline__ int crow(int r, int hi) { return (r & 3) + 8 * (r >> 2) + 4 * hi; }
; #define AB_LOAD(jj) do { const long o_ = (long)(tc0 + (jj)) * 64 * 1024; kreg0 = *(const u32x4*)(kbase + o_); vreg0 = *(const u32x4*)(vbase + o_); kreg1 = *(const u32x4*)(kbase + o_ + 64); vreg1 = *(const u32x4*)(vbase + o_ + 64); } while (0)
; __device__ __forceinline__ void attn_block_unit(LAS unsigned char* lds, const bf16* QB, bf16* OB, const bf16* KB, const bf16* VB, int sb, int hp, int cp, const float* tab, int tid) {
;     ...
;         __syncthreads();
;         if (j + 1 < 10) AB_LOAD(j + 1);
;         const int t = j - csel;
;         if (t >= 0 && t < 9) {
;             LAS const unsigned char* kb = lds + (j & 1) * AB_BUF + hsel * AB_HB; LAS const unsigned char* vb = kb + 9216;
;             f32x16 s0, s1;
; #pragma unroll
;             for (int r = 0; r < 16; ++r) { s0[r] = 0.f; s1[r] = 0.f; }
; #pragma unroll
;             for (int d0 = 0; d0 < 4; ++d0) {
;                 const bf16x8 k0 = *(const LAS bf16x8*)(kb + r32 * ATT_VP + (16 * d0 + 8 * hi) * 2), k1 = *(const LAS bf16x8*)(kb + (32 + r32) * ATT_VP + (16 * d0 + 8 * hi) * 2);
;                 s0 = __builtin_amdgcn_mfma_f32_32x32x16_bf16(k0, qfr[d0], s0, 0, 0, 0); s1 = __builtin_amdgcn_mfma_f32_32x32x16_bf16(k1, qfr[d0], s1, 0, 0, 0); }
;             if (t < 6) {
; #pragma unroll
;                 for (int r = 0; r < 16; ++r) { s0[r] += cb; s1[r] += cb; }
;             } else {
;                 const int relb = 64 * (8 - t) + 32 * qh + r32 + 128;
; #pragma unroll
;                 for (int r = 0; r < 16; ++r) { const int i0 = relb - crow(r, hi); s0[r] += btab[i0 > 256 ? 256 : i0]; const int i1 = i0 - 32; s1[r] += btab[i1 > 256 ? 256 : i1]; }
;             }
.LBB0_550:
	s_bitcmp1_b32 s6, 0
	s_cselect_b32 s26, 0x9000, 0
	s_add_i32 s30, s28, s26
	v_add3_u32 v2, s30, v167, v138
	ds_read_b128 v[36:39], v2
	ds_read_b128 v[52:55], v2 offset:4608
	ds_read_b128 v[40:43], v2 offset:32
	ds_read_b128 v[56:59], v2 offset:4640
	ds_read_b128 v[44:47], v2 offset:64
	ds_read_b128 v[60:63], v2 offset:4672
	ds_read_b128 v[48:51], v2 offset:96
	ds_read_b128 v[64:67], v2 offset:4704
	v_add3_u32 v2, s30, v161, v163
	s_waitcnt lgkmcnt(7)
	v_mfma_f32_32x32x16_bf16 v[84:99], v[36:39], v[104:107], 0
	s_waitcnt lgkmcnt(6)
	v_mfma_f32_32x32x16_bf16 v[68:83], v[52:55], v[104:107], 0
	s_waitcnt lgkmcnt(5)
	v_mfma_f32_32x32x16_bf16 v[84:99], v[40:43], v[108:111], v[84:99]
	s_waitcnt lgkmcnt(4)
	v_mfma_f32_32x32x16_bf16 v[68:83], v[56:59], v[108:111], v[68:83]
	s_waitcnt lgkmcnt(3)
	v_mfma_f32_32x32x16_bf16 v[84:99], v[44:47], v[120:123], v[84:99]
	s_waitcnt lgkmcnt(2)
	v_mfma_f32_32x32x16_bf16 v[68:83], v[60:63], v[120:123], v[68:83]
	s_waitcnt lgkmcnt(1)
	v_mfma_f32_32x32x16_bf16 v[84:99], v[48:51], v[124:127], v[84:99]
	s_waitcnt lgkmcnt(0)
	v_mfma_f32_32x32x16_bf16 v[68:83], v[64:67], v[124:127], v[68:83]
	ds_read_b64_tr_b16 v[218:219], v2 offset:9216
	ds_read_b64_tr_b16 v[220:221], v2 offset:10368
	ds_read_b64_tr_b16 v[222:223], v2 offset:11520
	ds_read_b64_tr_b16 v[224:225], v2 offset:12672
	ds_read_b64_tr_b16 v[226:227], v2 offset:13824
	ds_read_b64_tr_b16 v[228:229], v2 offset:14976
	ds_read_b64_tr_b16 v[230:231], v2 offset:16128
	ds_read_b64_tr_b16 v[232:233], v2 offset:17280
	ds_read_b64_tr_b16 v[234:235], v2 offset:9280
	ds_read_b64_tr_b16 v[236:237], v2 offset:10432
	ds_read_b64_tr_b16 v[238:239], v2 offset:11584
	ds_read_b64_tr_b16 v[240:241], v2 offset:12736
	ds_read_b64_tr_b16 v[242:243], v2 offset:13888
	ds_read_b64_tr_b16 v[244:245], v2 offset:15040
	ds_read_b64_tr_b16 v[246:247], v2 offset:16192
	ds_read_b64_tr_b16 v[248:249], v2 offset:17344
	s_cmp_gt_u32 s31, 5
	s_cbranch_scc0 .Latt_t_lt6
	v_add_u32_e32 v2, v135, v213
	v_add_u32_e32 v36, 0x280, v2
	v_min_i32_e32 v37, 0x100, v36
	v_min_i32_e32 v36, 0x120, v36
	v_lshl_add_u32 v36, v36, 2, s2
	v_add_u32_e32 v2, 0x27f, v2
	v_add_u32_e32 v38, 0xffffff80, v36
	v_min_i32_e32 v36, 0x100, v2
	v_add_u32_e32 v48, v135, v189
	v_lshl_add_u32 v39, v36, 2, s2
	v_add_u32_e32 v36, 0x27e, v48
	v_min_i32_e32 v40, 0x100, v36
	v_min_i32_e32 v36, 0x120, v36
	v_lshl_add_u32 v36, v36, 2, s2
	v_add_u32_e32 v41, 0xffffff80, v36
	v_add_u32_e32 v36, 0x27d, v48
	v_min_i32_e32 v2, 0x120, v2
	v_min_i32_e32 v42, 0x100, v36
	v_min_i32_e32 v36, 0x120, v36
	v_lshl_add_u32 v37, v37, 2, s2
	v_lshl_add_u32 v2, v2, 2, s2
	v_lshl_add_u32 v36, v36, 2, s2
	v_add_u32_e32 v2, 0xffffff80, v2
	v_lshl_add_u32 v40, v40, 2, s2
	v_lshl_add_u32 v42, v42, 2, s2
	v_add_u32_e32 v43, 0xffffff80, v36
	ds_read_b32 v36, v37
	ds_read_b32 v52, v38
	ds_read_b32 v37, v39
	ds_read_b32 v53, v2
	ds_read_b32 v38, v40
	ds_read_b32 v54, v41
	ds_read_b32 v39, v42
	ds_read_b32 v55, v43
	v_add_u32_e32 v41, 0x277, v48
	v_min_i32_e32 v42, 0x100, v41
	v_min_i32_e32 v41, 0x120, v41
	v_lshl_add_u32 v41, v41, 2, s2
	v_add_u32_e32 v43, 0xffffff80, v41
	v_add_u32_e32 v41, 0x276, v48
	v_min_i32_e32 v44, 0x100, v41
	v_min_i32_e32 v41, 0x120, v41
	v_lshl_add_u32 v41, v41, 2, s2
	v_add_u32_e32 v2, 0x278, v48
	v_add_u32_e32 v45, 0xffffff80, v41
	v_add_u32_e32 v41, 0x275, v48
	v_min_i32_e32 v40, 0x100, v2
	v_min_i32_e32 v2, 0x120, v2
	v_min_i32_e32 v46, 0x100, v41
	v_min_i32_e32 v41, 0x120, v41
	v_lshl_add_u32 v40, v40, 2, s2
	v_lshl_add_u32 v2, v2, 2, s2
	v_lshl_add_u32 v42, v42, 2, s2
	v_lshl_add_u32 v41, v41, 2, s2
	v_add_u32_e32 v2, 0xffffff80, v2
	v_lshl_add_u32 v44, v44, 2, s2
	v_lshl_add_u32 v46, v46, 2, s2
	v_add_u32_e32 v47, 0xffffff80, v41
	ds_read_b32 v40, v40
	ds_read_b32 v56, v2
	ds_read_b32 v41, v42
	ds_read_b32 v57, v43
	ds_read_b32 v42, v44
	ds_read_b32 v58, v45
	ds_read_b32 v43, v46
	ds_read_b32 v59, v47
	v_add_u32_e32 v45, 0x26f, v48
	v_min_i32_e32 v46, 0x100, v45
	v_min_i32_e32 v45, 0x120, v45
	v_lshl_add_u32 v45, v45, 2, s2
	v_add_u32_e32 v47, 0xffffff80, v45
	v_add_u32_e32 v45, 0x26e, v48
	v_min_i32_e32 v49, 0x100, v45
	v_min_i32_e32 v45, 0x120, v45
	v_lshl_add_u32 v45, v45, 2, s2
	v_add_u32_e32 v50, 0xffffff80, v45
	v_add_u32_e32 v45, 0x26d, v48
	v_add_u32_e32 v2, 0x270, v48
	v_min_i32_e32 v51, 0x100, v45
	v_min_i32_e32 v45, 0x120, v45
	v_min_i32_e32 v44, 0x100, v2
	v_min_i32_e32 v2, 0x120, v2
	v_lshl_add_u32 v45, v45, 2, s2
	v_lshl_add_u32 v44, v44, 2, s2
	v_lshl_add_u32 v2, v2, 2, s2
	v_lshl_add_u32 v46, v46, 2, s2
	v_add_u32_e32 v63, 0xffffff80, v45
	v_add_u32_e32 v2, 0xffffff80, v2
	v_lshl_add_u32 v49, v49, 2, s2
	v_lshl_add_u32 v51, v51, 2, s2
	ds_read_b32 v44, v44
	ds_read_b32 v60, v2
	ds_read_b32 v45, v46
	ds_read_b32 v61, v47
	ds_read_b32 v46, v49
	ds_read_b32 v62, v50
	ds_read_b32 v47, v51
	ds_read_b32 v63, v63
	v_add_u32_e32 v50, 0x267, v48
	v_min_i32_e32 v51, 0x100, v50
	v_min_i32_e32 v50, 0x120, v50
	v_lshl_add_u32 v50, v50, 2, s2
	v_add_u32_e32 v191, 0xffffff80, v50
	v_add_u32_e32 v50, 0x266, v48
	v_lshl_add_u32 v65, v51, 2, s2
	v_min_i32_e32 v51, 0x100, v50
	v_min_i32_e32 v50, 0x120, v50
	v_add_u32_e32 v2, 0x268, v48
	v_lshl_add_u32 v50, v50, 2, s2
	v_add_u32_e32 v48, 0x265, v48
	v_min_i32_e32 v49, 0x100, v2
	v_min_i32_e32 v2, 0x120, v2
	v_add_u32_e32 v66, 0xffffff80, v50
	v_min_i32_e32 v50, 0x100, v48
	v_min_i32_e32 v48, 0x120, v48
	v_lshl_add_u32 v49, v49, 2, s2
	v_lshl_add_u32 v2, v2, 2, s2
	v_lshl_add_u32 v51, v51, 2, s2
	v_lshl_add_u32 v67, v50, 2, s2
	v_lshl_add_u32 v48, v48, 2, s2
	v_add_u32_e32 v2, 0xffffff80, v2
	v_add_u32_e32 v216, 0xffffff80, v48
	ds_read_b32 v48, v49
	ds_read_b32 v64, v2
	ds_read_b32 v50, v51
	ds_read_b32 v51, v67
	ds_read_b32 v49, v65
	ds_read_b32 v67, v216
	ds_read_b32 v66, v66
	ds_read_b32 v65, v191
	s_waitcnt lgkmcnt(4)
	v_pk_add_f32 v[98:99], v[98:99], v[50:51]
	s_waitcnt lgkmcnt(3)
	v_pk_add_f32 v[96:97], v[96:97], v[48:49]
	v_pk_add_f32 v[94:95], v[94:95], v[46:47]
	v_pk_add_f32 v[92:93], v[92:93], v[44:45]
	v_pk_add_f32 v[90:91], v[90:91], v[42:43]
	v_pk_add_f32 v[88:89], v[88:89], v[40:41]
	v_pk_add_f32 v[86:87], v[86:87], v[38:39]
	v_pk_add_f32 v[84:85], v[84:85], v[36:37]
	s_waitcnt lgkmcnt(1)
	v_pk_add_f32 v[82:83], v[82:83], v[66:67]
	s_waitcnt lgkmcnt(0)
	v_pk_add_f32 v[80:81], v[80:81], v[64:65]
	v_pk_add_f32 v[78:79], v[78:79], v[62:63]
	v_pk_add_f32 v[76:77], v[76:77], v[60:61]
	v_pk_add_f32 v[74:75], v[74:75], v[58:59]
	v_pk_add_f32 v[72:73], v[72:73], v[56:57]
	v_pk_add_f32 v[70:71], v[70:71], v[54:55]
	v_pk_add_f32 v[68:69], v[68:69], v[52:53]
	v_mov_b32_e32 v66, 0
	s_branch .Latt_softmax
; #define LAS __attribute__((address_space(3)))
; __device__ __forceinline__ int crow(int r, int hi) { return (r & 3) + 8 * (r >> 2) + 4 * hi; }
; __device__ __forceinline__ bf16x8 cat8(s16x4 a, s16x4 b) { return (bf16x8){a[0], a[1], a[2], a[3], b[0], b[1], b[2], b[3]}; }
; __device__ __forceinline__ bf16x8 pack8(const f32x16& v, int o) { u32x4 w; w.x = pk2(v[o], v[o + 1]); w.y = pk2(v[o + 2], v[o + 3]); w.z = pk2(v[o + 4], v[o + 5]); w.w = pk2(v[o + 6], v[o + 7]); return __builtin_bit_cast(bf16x8, w); }
; __device__ __forceinline__ void attn_block_unit(LAS unsigned char* lds, const bf16* QB, bf16* OB, const bf16* KB, const bf16* VB, int sb, int hp, int cp, const float* tab, int tid) {
;     ...
;             if (t < 6) {
; #pragma unroll
;                 for (int r = 0; r < 16; ++r) { s0[r] += cb; s1[r] += cb; }
;             } else {
;                 const int relb = 64 * (8 - t) + 32 * qh + r32 + 128;
; #pragma unroll
;                 for (int r = 0; r < 16; ++r) { const int i0 = relb - crow(r, hi); s0[r] += btab[i0 > 256 ? 256 : i0]; const int i1 = i0 - 32; s1[r] += btab[i1 > 256 ? 256 : i1]; }
;             }
;             float tm = fmaxf(s0[0], s1[0]);
; #pragma unroll
;             for (int r = 1; r < 16; ++r) tm = fmaxf(tm, fmaxf(s0[r], s1[r]));
;             tm = fmaxf(tm, __shfl_xor(tm, 32));
;             const float mn = fmaxf(mrun, tm), sc = __expf(mrun - mn); mrun = mn;
;             float ps = 0.f;
; #pragma unroll
;             for (int r = 0; r < 16; ++r) { s0[r] = __expf(s0[r] - mn); s1[r] = __expf(s1[r] - mn); ps += s0[r] + s1[r]; }
;             lrun = lrun * sc + ps;
; #pragma unroll
;             for (int r = 0; r < 16; ++r) { oT[0][r] *= sc; oT[1][r] *= sc; }
;             bf16x8 pf[4]; pf[0] = pack8(s0, 0); pf[1] = pack8(s0, 8); pf[2] = pack8(s1, 0); pf[3] = pack8(s1, 8);
; #pragma unroll
;             for (int dh = 0; dh < 2; ++dh)
; #pragma unroll
;                 for (int kc = 0; kc < 4; ++kc) {
;                     LAS const unsigned char* p = vb + traddr + (16 * kc) * ATT_VP + dh * 64;
;                     const bf16x8 vf = cat8(tr16(p), tr16(p + 8 * ATT_VP));
;                     oT[dh] = __builtin_amdgcn_mfma_f32_32x32x16_bf16(vf, pf[kc], oT[dh], 0, 0, 0);
;                 }
.Latt_t_lt6:
	v_mov_b32_e32 v66, v190
.Latt_softmax:
	v_max3_f32 v36, v84, v85, v86
	v_max3_f32 v37, v87, v88, v89
	v_max3_f32 v38, v90, v91, v92
	v_max3_f32 v39, v93, v94, v95
	v_max3_f32 v40, v96, v97, v98
	v_max3_f32 v41, v99, v68, v69
	v_max3_f32 v42, v70, v71, v72
	v_max3_f32 v43, v73, v74, v75
	v_max3_f32 v44, v76, v77, v78
	v_max3_f32 v45, v79, v80, v81
	v_max3_f32 v46, v82, v83, v36
	v_max3_f32 v37, v37, v38, v39
	v_max3_f32 v40, v40, v41, v42
	v_max3_f32 v43, v43, v44, v45
	v_max3_f32 v37, v37, v40, v43
	v_max_f32_e32 v64, v37, v46
	ds_bpermute_b32 v65, v200, v64
	s_waitcnt lgkmcnt(0)
	v_max_f32_e32 v64, v64, v65
	v_add_f32_e32 v64, v64, v66
	v_max_f32_e32 v67, v215, v64
	v_sub_f32_e32 v63, v215, v67
	v_sub_f32_e32 v62, v66, v67
	v_mul_f32_e32 v63, 0x3fb8aa3b, v63
	v_mul_f32_e32 v62, 0x3fb8aa3b, v62
	v_exp_f32_e32 v52, v63
	v_mov_b32_e32 v215, v67
	v_fmamk_f32 v84, v84, 0x3fb8aa3b, v62
	v_fmamk_f32 v85, v85, 0x3fb8aa3b, v62
	v_fmamk_f32 v86, v86, 0x3fb8aa3b, v62
	v_fmamk_f32 v87, v87, 0x3fb8aa3b, v62
	v_fmamk_f32 v88, v88, 0x3fb8aa3b, v62
	v_fmamk_f32 v89, v89, 0x3fb8aa3b, v62
	v_fmamk_f32 v90, v90, 0x3fb8aa3b, v62
	v_fmamk_f32 v91, v91, 0x3fb8aa3b, v62
	v_fmamk_f32 v92, v92, 0x3fb8aa3b, v62
	v_fmamk_f32 v93, v93, 0x3fb8aa3b, v62
	v_fmamk_f32 v94, v94, 0x3fb8aa3b, v62
	v_fmamk_f32 v95, v95, 0x3fb8aa3b, v62
	v_fmamk_f32 v96, v96, 0x3fb8aa3b, v62
	v_fmamk_f32 v97, v97, 0x3fb8aa3b, v62
	v_fmamk_f32 v98, v98, 0x3fb8aa3b, v62
	v_fmamk_f32 v99, v99, 0x3fb8aa3b, v62
	v_fmamk_f32 v68, v68, 0x3fb8aa3b, v62
	v_fmamk_f32 v69, v69, 0x3fb8aa3b, v62
	v_fmamk_f32 v70, v70, 0x3fb8aa3b, v62
	v_fmamk_f32 v71, v71, 0x3fb8aa3b, v62
	v_fmamk_f32 v72, v72, 0x3fb8aa3b, v62
	v_fmamk_f32 v73, v73, 0x3fb8aa3b, v62
	v_fmamk_f32 v74, v74, 0x3fb8aa3b, v62
	v_fmamk_f32 v75, v75, 0x3fb8aa3b, v62
	v_fmamk_f32 v76, v76, 0x3fb8aa3b, v62
	v_fmamk_f32 v77, v77, 0x3fb8aa3b, v62
	v_fmamk_f32 v78, v78, 0x3fb8aa3b, v62
	v_fmamk_f32 v79, v79, 0x3fb8aa3b, v62
	v_fmamk_f32 v80, v80, 0x3fb8aa3b, v62
	v_fmamk_f32 v81, v81, 0x3fb8aa3b, v62
	v_fmamk_f32 v82, v82, 0x3fb8aa3b, v62
	v_fmamk_f32 v83, v83, 0x3fb8aa3b, v62
	v_exp_f32_e32 v84, v84
	v_exp_f32_e32 v85, v85
	v_exp_f32_e32 v86, v86
	v_exp_f32_e32 v87, v87
	v_exp_f32_e32 v88, v88
	v_exp_f32_e32 v89, v89
	v_exp_f32_e32 v90, v90
	v_exp_f32_e32 v91, v91
	v_exp_f32_e32 v92, v92
	v_exp_f32_e32 v93, v93
	v_exp_f32_e32 v94, v94
	v_exp_f32_e32 v95, v95
	v_exp_f32_e32 v96, v96
	v_exp_f32_e32 v97, v97
	v_exp_f32_e32 v98, v98
	v_exp_f32_e32 v99, v99
	v_exp_f32_e32 v68, v68
	v_exp_f32_e32 v69, v69
	v_exp_f32_e32 v70, v70
	v_exp_f32_e32 v71, v71
	v_exp_f32_e32 v72, v72
	v_exp_f32_e32 v73, v73
	v_exp_f32_e32 v74, v74
	v_exp_f32_e32 v75, v75
	v_exp_f32_e32 v76, v76
	v_exp_f32_e32 v77, v77
	v_exp_f32_e32 v78, v78
	v_exp_f32_e32 v79, v79
	v_exp_f32_e32 v80, v80
	v_exp_f32_e32 v81, v81
	v_exp_f32_e32 v82, v82
	v_exp_f32_e32 v83, v83
	v_pk_add_f32 v[36:37], v[84:85], v[86:87]
	v_pk_add_f32 v[38:39], v[88:89], v[90:91]
	v_pk_add_f32 v[40:41], v[92:93], v[94:95]
	v_pk_add_f32 v[42:43], v[96:97], v[98:99]
	v_pk_add_f32 v[44:45], v[68:69], v[70:71]
	v_pk_add_f32 v[46:47], v[72:73], v[74:75]
	v_pk_add_f32 v[48:49], v[76:77], v[78:79]
	v_pk_add_f32 v[50:51], v[80:81], v[82:83]
	v_pk_add_f32 v[54:55], v[36:37], v[38:39]
	v_pk_add_f32 v[56:57], v[40:41], v[42:43]
	v_pk_add_f32 v[58:59], v[44:45], v[46:47]
	v_pk_add_f32 v[60:61], v[48:49], v[50:51]
	v_pk_add_f32 v[54:55], v[54:55], v[56:57]
	v_pk_add_f32 v[58:59], v[58:59], v[60:61]
	v_pk_add_f32 v[54:55], v[54:55], v[58:59]
	v_add_f32_e32 v54, v54, v55
	v_fma_f32 v214, v214, v52, v54
	v_pk_mul_f32 v[34:35], v[34:35], v[52:53] op_sel_hi:[1,0]
	v_pk_mul_f32 v[32:33], v[32:33], v[52:53] op_sel_hi:[1,0]
	v_pk_mul_f32 v[30:31], v[30:31], v[52:53] op_sel_hi:[1,0]
	v_pk_mul_f32 v[28:29], v[28:29], v[52:53] op_sel_hi:[1,0]
	v_pk_mul_f32 v[26:27], v[26:27], v[52:53] op_sel_hi:[1,0]
	v_pk_mul_f32 v[24:25], v[24:25], v[52:53] op_sel_hi:[1,0]
	v_pk_mul_f32 v[22:23], v[22:23], v[52:53] op_sel_hi:[1,0]
	v_pk_mul_f32 v[20:21], v[20:21], v[52:53] op_sel_hi:[1,0]
	v_pk_mul_f32 v[18:19], v[18:19], v[52:53] op_sel_hi:[1,0]
	v_pk_mul_f32 v[16:17], v[16:17], v[52:53] op_sel_hi:[1,0]
	v_pk_mul_f32 v[14:15], v[14:15], v[52:53] op_sel_hi:[1,0]
	v_pk_mul_f32 v[12:13], v[12:13], v[52:53] op_sel_hi:[1,0]
	v_pk_mul_f32 v[10:11], v[10:11], v[52:53] op_sel_hi:[1,0]
	v_pk_mul_f32 v[8:9], v[8:9], v[52:53] op_sel_hi:[1,0]
	v_pk_mul_f32 v[6:7], v[6:7], v[52:53] op_sel_hi:[1,0]
	v_pk_mul_f32 v[4:5], v[4:5], v[52:53] op_sel_hi:[1,0]
	v_cvt_pk_bf16_f32 v36, v84, v85
	v_cvt_pk_bf16_f32 v37, v86, v87
	v_cvt_pk_bf16_f32 v38, v88, v89
	v_cvt_pk_bf16_f32 v39, v90, v91
	v_cvt_pk_bf16_f32 v40, v92, v93
	v_cvt_pk_bf16_f32 v41, v94, v95
	v_cvt_pk_bf16_f32 v42, v96, v97
	v_cvt_pk_bf16_f32 v43, v98, v99
	v_cvt_pk_bf16_f32 v44, v68, v69
	v_cvt_pk_bf16_f32 v45, v70, v71
	v_cvt_pk_bf16_f32 v46, v72, v73
	v_cvt_pk_bf16_f32 v47, v74, v75
	v_cvt_pk_bf16_f32 v48, v76, v77
	v_cvt_pk_bf16_f32 v49, v78, v79
	v_cvt_pk_bf16_f32 v50, v80, v81
	v_cvt_pk_bf16_f32 v51, v82, v83
	s_waitcnt lgkmcnt(0)
	v_mfma_f32_32x32x16_bf16 v[20:35], v[218:221], v[36:39], v[20:35]
	v_mfma_f32_32x32x16_bf16 v[4:19], v[234:237], v[36:39], v[4:19]
	v_mfma_f32_32x32x16_bf16 v[20:35], v[222:225], v[40:43], v[20:35]
	v_mfma_f32_32x32x16_bf16 v[4:19], v[238:241], v[40:43], v[4:19]
	v_mfma_f32_32x32x16_bf16 v[20:35], v[226:229], v[44:47], v[20:35]
	v_mfma_f32_32x32x16_bf16 v[4:19], v[242:245], v[44:47], v[4:19]
	v_mfma_f32_32x32x16_bf16 v[20:35], v[230:233], v[48:51], v[20:35]
	v_mfma_f32_32x32x16_bf16 v[4:19], v[246:249], v[48:51], v[4:19]
	s_andn2_b64 vcc, exec, s[14:15]
	s_add_i32 s14, s6, 1
	s_cbranch_vccz .LBB0_546
	s_branch .LBB0_547
